# code placement: GU/DN/OUT/IN K-loop heads aligned to 64 bytes (s_nop pad)
# speedup vs baseline: 1.0243x; 1.0093x over previous
; DI void zero_acc(f32x4 (&acc)[4][4]) {
; #pragma unroll
;     for (int i = 0; i < 4; ++i)
; #pragma unroll
;         for (int j = 0; j < 4; ++j) acc[i][j] = (f32x4){0.f, 0.f, 0.f, 0.f};
; }
; DI void gemm_gu(const Params& p, size_t woff, int bid, int nb, char* smem, const int tid) {
;     ...
;     for (; have; tm = tm2, tn = tn2) {
;         have = ti.next(tm2, tn2);
;         const int m0 = tm * 256, n0 = tn * 128;
;         f32x4 acc[4][4]; zero_acc(acc);
;         gemm_stream(A, 1024, Bt, 1024, 1024, m0, n0, have, tm2 * 256, tn2 * 128, smem, acc, tid, rg);
.Lgu_nonext:
	v_mov_b64_e32 v[24:25], 0
	v_mov_b64_e32 v[26:27], 0
	v_mov_b64_e32 v[28:29], 0
	v_mov_b64_e32 v[30:31], 0
	v_mov_b64_e32 v[32:33], 0
	v_mov_b64_e32 v[34:35], 0
	v_mov_b64_e32 v[36:37], 0
	v_mov_b64_e32 v[38:39], 0
	v_mov_b64_e32 v[40:41], 0
	v_mov_b64_e32 v[42:43], 0
	v_mov_b64_e32 v[44:45], 0
	v_mov_b64_e32 v[46:47], 0
	v_mov_b64_e32 v[48:49], 0
	v_mov_b64_e32 v[50:51], 0
	v_mov_b64_e32 v[52:53], 0
	v_mov_b64_e32 v[54:55], 0
	v_mov_b64_e32 v[56:57], 0
	v_mov_b64_e32 v[58:59], 0
	v_mov_b64_e32 v[60:61], 0
	v_mov_b64_e32 v[62:63], 0
	v_mov_b64_e32 v[64:65], 0
	v_mov_b64_e32 v[66:67], 0
	v_mov_b64_e32 v[68:69], 0
	v_mov_b64_e32 v[70:71], 0
	v_mov_b64_e32 v[72:73], 0
	v_mov_b64_e32 v[74:75], 0
	v_mov_b64_e32 v[76:77], 0
	v_mov_b64_e32 v[78:79], 0
	v_mov_b64_e32 v[80:81], 0
	v_mov_b64_e32 v[82:83], 0
	v_mov_b64_e32 v[84:85], 0
	v_mov_b64_e32 v[86:87], 0
	v_mov_b64_e32 v[88:89], 0
	v_mov_b64_e32 v[90:91], 0
	v_mov_b64_e32 v[92:93], 0
	v_mov_b64_e32 v[94:95], 0
	v_mov_b64_e32 v[96:97], 0
	v_mov_b64_e32 v[98:99], 0
	v_mov_b64_e32 v[100:101], 0
	v_mov_b64_e32 v[102:103], 0
	v_mov_b64_e32 v[104:105], 0
	v_mov_b64_e32 v[106:107], 0
	v_mov_b64_e32 v[108:109], 0
	v_mov_b64_e32 v[110:111], 0
	v_mov_b64_e32 v[112:113], 0
	v_mov_b64_e32 v[114:115], 0
	v_mov_b64_e32 v[116:117], 0
	v_mov_b64_e32 v[118:119], 0
	v_mov_b64_e32 v[120:121], 0
	v_mov_b64_e32 v[122:123], 0
	v_mov_b64_e32 v[124:125], 0
	v_mov_b64_e32 v[126:127], 0
	v_mov_b64_e32 v[128:129], 0
	v_mov_b64_e32 v[130:131], 0
	v_mov_b64_e32 v[132:133], 0
	v_mov_b64_e32 v[134:135], 0
	v_mov_b64_e32 v[136:137], 0
	v_mov_b64_e32 v[138:139], 0
	v_mov_b64_e32 v[140:141], 0
	v_mov_b64_e32 v[142:143], 0
	v_mov_b64_e32 v[144:145], 0
	v_mov_b64_e32 v[146:147], 0
	v_mov_b64_e32 v[148:149], 0
	v_mov_b64_e32 v[150:151], 0
	s_add_u32 s0, s54, 7
	.p2alignl 6, 3212836864

; DI void zero_acc(f32x4 (&acc)[4][4]) {
; #pragma unroll
;     for (int i = 0; i < 4; ++i)
; #pragma unroll
;         for (int j = 0; j < 4; ++j) acc[i][j] = (f32x4){0.f, 0.f, 0.f, 0.f};
; }
; DI void gemm_y(const Params& p, const bf16_t* A, int lda, size_t woff, int K, int kper, int bid, int nb, char* smem, const int tid) {
;     ...
;     for (; have; tm = tm2, tn = tn2) {
;         have = ti.next(tm2, tn2);
;         const int m0 = tm * 256, n0 = tn * 128;
;         f32x4 acc[4][4]; zero_acc(acc);
;         gemm_stream(A, lda, Bt, K, K, m0, n0, have, tm2 * 256, tn2 * 128, smem, acc, tid, rg);
;         epi_y<0>(p, acc, m0, n0, tid);
;     }
;     const int S = (K / 64) / kper;
;     for (int u = bid; u < 8 * S; u += nb) {
;         const int tile = u / S, part = u - tile * S, m0 = NP, n0 = tile * 128;
;         f32x4 acc[4][4]; zero_acc(acc);
;         gemm_mainloop(A + part * kper * 64, lda, Bt + part * kper * 64, K, kper * 64, m0, n0, smem, acc, tid);
.Lgyd_nx_done:
	v_mov_b64_e32 v[24:25], 0
	v_mov_b64_e32 v[26:27], 0
	v_mov_b64_e32 v[28:29], 0
	v_mov_b64_e32 v[30:31], 0
	v_mov_b64_e32 v[32:33], 0
	v_mov_b64_e32 v[34:35], 0
	v_mov_b64_e32 v[36:37], 0
	v_mov_b64_e32 v[38:39], 0
	v_mov_b64_e32 v[40:41], 0
	v_mov_b64_e32 v[42:43], 0
	v_mov_b64_e32 v[44:45], 0
	v_mov_b64_e32 v[46:47], 0
	v_mov_b64_e32 v[48:49], 0
	v_mov_b64_e32 v[50:51], 0
	v_mov_b64_e32 v[52:53], 0
	v_mov_b64_e32 v[54:55], 0
	v_mov_b64_e32 v[56:57], 0
	v_mov_b64_e32 v[58:59], 0
	v_mov_b64_e32 v[60:61], 0
	v_mov_b64_e32 v[62:63], 0
	v_mov_b64_e32 v[64:65], 0
	v_mov_b64_e32 v[66:67], 0
	v_mov_b64_e32 v[68:69], 0
	v_mov_b64_e32 v[70:71], 0
	v_mov_b64_e32 v[72:73], 0
	v_mov_b64_e32 v[74:75], 0
	v_mov_b64_e32 v[76:77], 0
	v_mov_b64_e32 v[78:79], 0
	v_mov_b64_e32 v[80:81], 0
	v_mov_b64_e32 v[82:83], 0
	v_mov_b64_e32 v[84:85], 0
	v_mov_b64_e32 v[86:87], 0
	v_mov_b64_e32 v[88:89], 0
	v_mov_b64_e32 v[90:91], 0
	v_mov_b64_e32 v[92:93], 0
	v_mov_b64_e32 v[94:95], 0
	v_mov_b64_e32 v[96:97], 0
	v_mov_b64_e32 v[98:99], 0
	v_mov_b64_e32 v[100:101], 0
	v_mov_b64_e32 v[102:103], 0
	v_mov_b64_e32 v[104:105], 0
	v_mov_b64_e32 v[106:107], 0
	v_mov_b64_e32 v[108:109], 0
	v_mov_b64_e32 v[110:111], 0
	v_mov_b64_e32 v[112:113], 0
	v_mov_b64_e32 v[114:115], 0
	v_mov_b64_e32 v[116:117], 0
	v_mov_b64_e32 v[118:119], 0
	v_mov_b64_e32 v[120:121], 0
	v_mov_b64_e32 v[122:123], 0
	v_mov_b64_e32 v[124:125], 0
	v_mov_b64_e32 v[126:127], 0
	v_mov_b64_e32 v[128:129], 0
	v_mov_b64_e32 v[130:131], 0
	v_mov_b64_e32 v[132:133], 0
	v_mov_b64_e32 v[134:135], 0
	v_mov_b64_e32 v[136:137], 0
	v_mov_b64_e32 v[138:139], 0
	v_mov_b64_e32 v[140:141], 0
	v_mov_b64_e32 v[142:143], 0
	v_mov_b64_e32 v[144:145], 0
	v_mov_b64_e32 v[146:147], 0
	v_mov_b64_e32 v[148:149], 0
	v_mov_b64_e32 v[150:151], 0
	s_cmp_eq_u32 s55, 0
	s_cselect_b32 s0, 21, 1
	s_add_u32 s0, s0, s54
	s_cmp_eq_u32 s0, 0
	s_cbranch_scc1 .Lgyd_kdone
	.p2alignl 6, 3212836864

; DI void zero_acc(f32x4 (&acc)[4][4]) {
; #pragma unroll
;     for (int i = 0; i < 4; ++i)
; #pragma unroll
;         for (int j = 0; j < 4; ++j) acc[i][j] = (f32x4){0.f, 0.f, 0.f, 0.f};
; }
; DI void gemm_y(const Params& p, const bf16_t* A, int lda, size_t woff, int K, int kper, int bid, int nb, char* smem, const int tid) {
;     ...
;     for (; have; tm = tm2, tn = tn2) {
;         have = ti.next(tm2, tn2);
;         const int m0 = tm * 256, n0 = tn * 128;
;         f32x4 acc[4][4]; zero_acc(acc);
;         gemm_stream(A, lda, Bt, K, K, m0, n0, have, tm2 * 256, tn2 * 128, smem, acc, tid, rg);
;         epi_y<0>(p, acc, m0, n0, tid);
;     }
;     const int S = (K / 64) / kper;
;     for (int u = bid; u < 8 * S; u += nb) {
;         const int tile = u / S, part = u - tile * S, m0 = NP, n0 = tile * 128;
;         f32x4 acc[4][4]; zero_acc(acc);
;         gemm_mainloop(A + part * kper * 64, lda, Bt + part * kper * 64, K, kper * 64, m0, n0, smem, acc, tid);
.Lgyo_nx_done:
	v_mov_b64_e32 v[24:25], 0
	v_mov_b64_e32 v[26:27], 0
	v_mov_b64_e32 v[28:29], 0
	v_mov_b64_e32 v[30:31], 0
	v_mov_b64_e32 v[32:33], 0
	v_mov_b64_e32 v[34:35], 0
	v_mov_b64_e32 v[36:37], 0
	v_mov_b64_e32 v[38:39], 0
	v_mov_b64_e32 v[40:41], 0
	v_mov_b64_e32 v[42:43], 0
	v_mov_b64_e32 v[44:45], 0
	v_mov_b64_e32 v[46:47], 0
	v_mov_b64_e32 v[48:49], 0
	v_mov_b64_e32 v[50:51], 0
	v_mov_b64_e32 v[52:53], 0
	v_mov_b64_e32 v[54:55], 0
	v_mov_b64_e32 v[56:57], 0
	v_mov_b64_e32 v[58:59], 0
	v_mov_b64_e32 v[60:61], 0
	v_mov_b64_e32 v[62:63], 0
	v_mov_b64_e32 v[64:65], 0
	v_mov_b64_e32 v[66:67], 0
	v_mov_b64_e32 v[68:69], 0
	v_mov_b64_e32 v[70:71], 0
	v_mov_b64_e32 v[72:73], 0
	v_mov_b64_e32 v[74:75], 0
	v_mov_b64_e32 v[76:77], 0
	v_mov_b64_e32 v[78:79], 0
	v_mov_b64_e32 v[80:81], 0
	v_mov_b64_e32 v[82:83], 0
	v_mov_b64_e32 v[84:85], 0
	v_mov_b64_e32 v[86:87], 0
	v_mov_b64_e32 v[88:89], 0
	v_mov_b64_e32 v[90:91], 0
	v_mov_b64_e32 v[92:93], 0
	v_mov_b64_e32 v[94:95], 0
	v_mov_b64_e32 v[96:97], 0
	v_mov_b64_e32 v[98:99], 0
	v_mov_b64_e32 v[100:101], 0
	v_mov_b64_e32 v[102:103], 0
	v_mov_b64_e32 v[104:105], 0
	v_mov_b64_e32 v[106:107], 0
	v_mov_b64_e32 v[108:109], 0
	v_mov_b64_e32 v[110:111], 0
	v_mov_b64_e32 v[112:113], 0
	v_mov_b64_e32 v[114:115], 0
	v_mov_b64_e32 v[116:117], 0
	v_mov_b64_e32 v[118:119], 0
	v_mov_b64_e32 v[120:121], 0
	v_mov_b64_e32 v[122:123], 0
	v_mov_b64_e32 v[124:125], 0
	v_mov_b64_e32 v[126:127], 0
	v_mov_b64_e32 v[128:129], 0
	v_mov_b64_e32 v[130:131], 0
	v_mov_b64_e32 v[132:133], 0
	v_mov_b64_e32 v[134:135], 0
	v_mov_b64_e32 v[136:137], 0
	v_mov_b64_e32 v[138:139], 0
	v_mov_b64_e32 v[140:141], 0
	v_mov_b64_e32 v[142:143], 0
	v_mov_b64_e32 v[144:145], 0
	v_mov_b64_e32 v[146:147], 0
	v_mov_b64_e32 v[148:149], 0
	v_mov_b64_e32 v[150:151], 0
	s_cmp_eq_u32 s55, 0
	s_cselect_b32 s0, 7, 0
	s_add_u32 s0, s0, s54
	s_cmp_eq_u32 s0, 0
	s_cbranch_scc1 .Lgyo_kdone
	.p2alignl 6, 3212836864
